# P8 final norm hand-written: all loads (h1 row, 8 slabs, norm_f) issued up front with one wait (compiler's loop re-loaded norm_f in three serial round trips)
# speedup vs baseline: 1.0033x; 1.0033x over previous
; DI float bflo(unsigned u) { return __uint_as_float(u << 16); }
; DI float bfhi(unsigned u) { return __uint_as_float(u & 0xffff0000u); }
; DI void final_norm(const Params& P, int G, int wave, int lane, float* dst) {
;     const int gw = blockIdx.x * 8 + wave, NGW = G * 8;
;     const bf16_t* h1b = (const bf16_t*)(P.ws + WS_H1B);
;     for (int m = MP + gw; m < MT; m += NGW) {
;         f32x4 v[4]; float s = 0.f;
; #pragma unroll
;         for (int j = 0; j < 4; ++j) { const u32x2 hb = *(const u32x2*)(h1b + (size_t)m * DM + 4 * lane + 256 * j); v[j] = (f32x4){bflo(hb.x), bfhi(hb.x), bflo(hb.y), bfhi(hb.y)}; }
;         const bf16_t* sl = (const bf16_t*)(P.ws + WS_SLAB) + (size_t)(m - MP) * DM + 4 * lane;
; #pragma unroll
;         for (int q = 0; q < NSPLIT_DN; ++q)
; #pragma unroll
;             for (int j = 0; j < 4; ++j) { const u32x2 sb = *(const u32x2*)(sl + (size_t)q * ((size_t)MS * DM) + 256 * j); v[j] += (f32x4){bflo(sb.x), bfhi(sb.x), bflo(sb.y), bfhi(sb.y)}; }
; #pragma unroll
;         for (int j = 0; j < 4; ++j) s += (v[j][0] * v[j][0] + v[j][1] * v[j][1]) + (v[j][2] * v[j][2] + v[j][3] * v[j][3]);
;         const float rs = rsqrtf(wave_sum(s) * (1.0f / DM) + EPS);
; #pragma unroll
;         for (int j = 0; j < 4; ++j) *(f32x4*)(dst + (size_t)m * DM + 4 * lane + 256 * j) = v[j] * rs * *(const f32x4*)(P.norm_f + 4 * lane + 256 * j);
.LBB0_1154:
	s_or_b64 exec, exec, s[0:1]
	s_add_i32 s2, s64, 0x4000
	s_cmpk_gt_i32 s2, 0x43ff
	s_waitcnt lgkmcnt(0)
	s_barrier
	s_cbranch_scc1 .LBB0_1157
	v_mbcnt_lo_u32_b32 v2, -1, 0
	v_mbcnt_hi_u32_b32 v2, -1, v2
	v_lshlrev_b32_e32 v0, 3, v2
	v_lshlrev_b32_e32 v1, 4, v2
	v_lshlrev_b32_e32 v3, 2, v2
	global_load_dwordx4 v[160:163], v1, s[60:61]
	global_load_dwordx4 v[164:167], v1, s[60:61] offset:1024
	global_load_dwordx4 v[168:171], v1, s[60:61] offset:2048
	global_load_dwordx4 v[172:175], v1, s[60:61] offset:3072
.Lp8_row:
	s_lshl_b32 s0, s64, 11
	s_add_u32 s4, s0, 0xfc00000
	s_add_u32 s4, s68, s4
	s_addc_u32 s5, s69, 0
	s_add_u32 s6, s0, 0xba00000
	s_add_u32 s6, s68, s6
	s_addc_u32 s7, s69, 0
	s_nop 0
	global_load_dwordx2 v[16:17], v0, s[4:5]
	global_load_dwordx2 v[18:19], v0, s[4:5] offset:512
	global_load_dwordx2 v[20:21], v0, s[4:5] offset:1024
	global_load_dwordx2 v[22:23], v0, s[4:5] offset:1536
	global_load_dwordx2 v[24:25], v0, s[6:7]
	global_load_dwordx2 v[26:27], v0, s[6:7] offset:512
	global_load_dwordx2 v[28:29], v0, s[6:7] offset:1024
	global_load_dwordx2 v[30:31], v0, s[6:7] offset:1536
	s_add_u32 s6, s6, 0x200000
	s_addc_u32 s7, s7, 0
	s_nop 0
	global_load_dwordx2 v[32:33], v0, s[6:7]
	global_load_dwordx2 v[34:35], v0, s[6:7] offset:512
	global_load_dwordx2 v[36:37], v0, s[6:7] offset:1024
	global_load_dwordx2 v[38:39], v0, s[6:7] offset:1536
	s_add_u32 s6, s6, 0x200000
	s_addc_u32 s7, s7, 0
	s_nop 0
	global_load_dwordx2 v[40:41], v0, s[6:7]
	global_load_dwordx2 v[42:43], v0, s[6:7] offset:512
	global_load_dwordx2 v[44:45], v0, s[6:7] offset:1024
	global_load_dwordx2 v[46:47], v0, s[6:7] offset:1536
	s_add_u32 s6, s6, 0x200000
	s_addc_u32 s7, s7, 0
	s_nop 0
	global_load_dwordx2 v[48:49], v0, s[6:7]
	global_load_dwordx2 v[50:51], v0, s[6:7] offset:512
	global_load_dwordx2 v[52:53], v0, s[6:7] offset:1024
	global_load_dwordx2 v[54:55], v0, s[6:7] offset:1536
	s_add_u32 s6, s6, 0x200000
	s_addc_u32 s7, s7, 0
	s_nop 0
	global_load_dwordx2 v[56:57], v0, s[6:7]
	global_load_dwordx2 v[58:59], v0, s[6:7] offset:512
	global_load_dwordx2 v[60:61], v0, s[6:7] offset:1024
	global_load_dwordx2 v[62:63], v0, s[6:7] offset:1536
	s_add_u32 s6, s6, 0x200000
	s_addc_u32 s7, s7, 0
	s_nop 0
	global_load_dwordx2 v[64:65], v0, s[6:7]
	global_load_dwordx2 v[66:67], v0, s[6:7] offset:512
	global_load_dwordx2 v[68:69], v0, s[6:7] offset:1024
	global_load_dwordx2 v[70:71], v0, s[6:7] offset:1536
	s_add_u32 s6, s6, 0x200000
	s_addc_u32 s7, s7, 0
	s_nop 0
	global_load_dwordx2 v[72:73], v0, s[6:7]
	global_load_dwordx2 v[74:75], v0, s[6:7] offset:512
	global_load_dwordx2 v[76:77], v0, s[6:7] offset:1024
	global_load_dwordx2 v[78:79], v0, s[6:7] offset:1536
	s_add_u32 s6, s6, 0x200000
	s_addc_u32 s7, s7, 0
	s_nop 0
	global_load_dwordx2 v[80:81], v0, s[6:7]
	global_load_dwordx2 v[82:83], v0, s[6:7] offset:512
	global_load_dwordx2 v[84:85], v0, s[6:7] offset:1024
	global_load_dwordx2 v[86:87], v0, s[6:7] offset:1536
	s_add_i32 s0, s64, 0x4000
	s_ashr_i32 s1, s0, 31
	s_lshl_b64 s[0:1], s[0:1], 12
	s_add_u32 s8, s62, s0
	s_addc_u32 s9, s63, s1
	s_waitcnt vmcnt(0)
	v_lshlrev_b32_e32 v200, 16, v16
	v_and_b32_e32 v201, 0xffff0000, v16
	v_lshlrev_b32_e32 v202, 16, v17
	v_and_b32_e32 v203, 0xffff0000, v17
	v_lshlrev_b32_e32 v204, 16, v18
	v_and_b32_e32 v205, 0xffff0000, v18
	v_lshlrev_b32_e32 v206, 16, v19
	v_and_b32_e32 v207, 0xffff0000, v19
	v_lshlrev_b32_e32 v208, 16, v20
	v_and_b32_e32 v209, 0xffff0000, v20
	v_lshlrev_b32_e32 v210, 16, v21
	v_and_b32_e32 v211, 0xffff0000, v21
	v_lshlrev_b32_e32 v212, 16, v22
	v_and_b32_e32 v213, 0xffff0000, v22
	v_lshlrev_b32_e32 v214, 16, v23
	v_and_b32_e32 v215, 0xffff0000, v23
	v_lshlrev_b32_e32 v180, 16, v24
	v_and_b32_e32 v181, 0xffff0000, v24
	v_pk_add_f32 v[200:201], v[200:201], v[180:181]
	v_lshlrev_b32_e32 v180, 16, v25
	v_and_b32_e32 v181, 0xffff0000, v25
	v_pk_add_f32 v[202:203], v[202:203], v[180:181]
	v_lshlrev_b32_e32 v180, 16, v26
	v_and_b32_e32 v181, 0xffff0000, v26
	v_pk_add_f32 v[204:205], v[204:205], v[180:181]
	v_lshlrev_b32_e32 v180, 16, v27
	v_and_b32_e32 v181, 0xffff0000, v27
	v_pk_add_f32 v[206:207], v[206:207], v[180:181]
	v_lshlrev_b32_e32 v180, 16, v28
	v_and_b32_e32 v181, 0xffff0000, v28
	v_pk_add_f32 v[208:209], v[208:209], v[180:181]
	v_lshlrev_b32_e32 v180, 16, v29
	v_and_b32_e32 v181, 0xffff0000, v29
	v_pk_add_f32 v[210:211], v[210:211], v[180:181]
	v_lshlrev_b32_e32 v180, 16, v30
	v_and_b32_e32 v181, 0xffff0000, v30
	v_pk_add_f32 v[212:213], v[212:213], v[180:181]
	v_lshlrev_b32_e32 v180, 16, v31
	v_and_b32_e32 v181, 0xffff0000, v31
	v_pk_add_f32 v[214:215], v[214:215], v[180:181]
	v_lshlrev_b32_e32 v180, 16, v32
	v_and_b32_e32 v181, 0xffff0000, v32
	v_pk_add_f32 v[200:201], v[200:201], v[180:181]
	v_lshlrev_b32_e32 v180, 16, v33
	v_and_b32_e32 v181, 0xffff0000, v33
	v_pk_add_f32 v[202:203], v[202:203], v[180:181]
	v_lshlrev_b32_e32 v180, 16, v34
	v_and_b32_e32 v181, 0xffff0000, v34
	v_pk_add_f32 v[204:205], v[204:205], v[180:181]
	v_lshlrev_b32_e32 v180, 16, v35
	v_and_b32_e32 v181, 0xffff0000, v35
	v_pk_add_f32 v[206:207], v[206:207], v[180:181]
	v_lshlrev_b32_e32 v180, 16, v36
	v_and_b32_e32 v181, 0xffff0000, v36
	v_pk_add_f32 v[208:209], v[208:209], v[180:181]
	v_lshlrev_b32_e32 v180, 16, v37
	v_and_b32_e32 v181, 0xffff0000, v37
	v_pk_add_f32 v[210:211], v[210:211], v[180:181]
	v_lshlrev_b32_e32 v180, 16, v38
	v_and_b32_e32 v181, 0xffff0000, v38
	v_pk_add_f32 v[212:213], v[212:213], v[180:181]
	v_lshlrev_b32_e32 v180, 16, v39
	v_and_b32_e32 v181, 0xffff0000, v39
	v_pk_add_f32 v[214:215], v[214:215], v[180:181]
	v_lshlrev_b32_e32 v180, 16, v40
	v_and_b32_e32 v181, 0xffff0000, v40
; DI float bflo(unsigned u) { return __uint_as_float(u << 16); }
; DI float bfhi(unsigned u) { return __uint_as_float(u & 0xffff0000u); }
; DI void final_norm(const Params& P, int G, int wave, int lane, float* dst) {
;     ...
;         for (int j = 0; j < 4; ++j) { const u32x2 hb = *(const u32x2*)(h1b + (size_t)m * DM + 4 * lane + 256 * j); v[j] = (f32x4){bflo(hb.x), bfhi(hb.x), bflo(hb.y), bfhi(hb.y)}; }
;         const bf16_t* sl = (const bf16_t*)(P.ws + WS_SLAB) + (size_t)(m - MP) * DM + 4 * lane;
; #pragma unroll
;         for (int q = 0; q < NSPLIT_DN; ++q)
; #pragma unroll
;             for (int j = 0; j < 4; ++j) { const u32x2 sb = *(const u32x2*)(sl + (size_t)q * ((size_t)MS * DM) + 256 * j); v[j] += (f32x4){bflo(sb.x), bfhi(sb.x), bflo(sb.y), bfhi(sb.y)}; }
; #pragma unroll
;         for (int j = 0; j < 4; ++j) s += (v[j][0] * v[j][0] + v[j][1] * v[j][1]) + (v[j][2] * v[j][2] + v[j][3] * v[j][3]);
;         const float rs = rsqrtf(wave_sum(s) * (1.0f / DM) + EPS);
	v_pk_add_f32 v[200:201], v[200:201], v[180:181]
	v_lshlrev_b32_e32 v180, 16, v41
	v_and_b32_e32 v181, 0xffff0000, v41
	v_pk_add_f32 v[202:203], v[202:203], v[180:181]
	v_lshlrev_b32_e32 v180, 16, v42
	v_and_b32_e32 v181, 0xffff0000, v42
	v_pk_add_f32 v[204:205], v[204:205], v[180:181]
	v_lshlrev_b32_e32 v180, 16, v43
	v_and_b32_e32 v181, 0xffff0000, v43
	v_pk_add_f32 v[206:207], v[206:207], v[180:181]
	v_lshlrev_b32_e32 v180, 16, v44
	v_and_b32_e32 v181, 0xffff0000, v44
	v_pk_add_f32 v[208:209], v[208:209], v[180:181]
	v_lshlrev_b32_e32 v180, 16, v45
	v_and_b32_e32 v181, 0xffff0000, v45
	v_pk_add_f32 v[210:211], v[210:211], v[180:181]
	v_lshlrev_b32_e32 v180, 16, v46
	v_and_b32_e32 v181, 0xffff0000, v46
	v_pk_add_f32 v[212:213], v[212:213], v[180:181]
	v_lshlrev_b32_e32 v180, 16, v47
	v_and_b32_e32 v181, 0xffff0000, v47
	v_pk_add_f32 v[214:215], v[214:215], v[180:181]
	v_lshlrev_b32_e32 v180, 16, v48
	v_and_b32_e32 v181, 0xffff0000, v48
	v_pk_add_f32 v[200:201], v[200:201], v[180:181]
	v_lshlrev_b32_e32 v180, 16, v49
	v_and_b32_e32 v181, 0xffff0000, v49
	v_pk_add_f32 v[202:203], v[202:203], v[180:181]
	v_lshlrev_b32_e32 v180, 16, v50
	v_and_b32_e32 v181, 0xffff0000, v50
	v_pk_add_f32 v[204:205], v[204:205], v[180:181]
	v_lshlrev_b32_e32 v180, 16, v51
	v_and_b32_e32 v181, 0xffff0000, v51
	v_pk_add_f32 v[206:207], v[206:207], v[180:181]
	v_lshlrev_b32_e32 v180, 16, v52
	v_and_b32_e32 v181, 0xffff0000, v52
	v_pk_add_f32 v[208:209], v[208:209], v[180:181]
	v_lshlrev_b32_e32 v180, 16, v53
	v_and_b32_e32 v181, 0xffff0000, v53
	v_pk_add_f32 v[210:211], v[210:211], v[180:181]
	v_lshlrev_b32_e32 v180, 16, v54
	v_and_b32_e32 v181, 0xffff0000, v54
	v_pk_add_f32 v[212:213], v[212:213], v[180:181]
	v_lshlrev_b32_e32 v180, 16, v55
	v_and_b32_e32 v181, 0xffff0000, v55
	v_pk_add_f32 v[214:215], v[214:215], v[180:181]
	v_lshlrev_b32_e32 v180, 16, v56
	v_and_b32_e32 v181, 0xffff0000, v56
	v_pk_add_f32 v[200:201], v[200:201], v[180:181]
	v_lshlrev_b32_e32 v180, 16, v57
	v_and_b32_e32 v181, 0xffff0000, v57
	v_pk_add_f32 v[202:203], v[202:203], v[180:181]
	v_lshlrev_b32_e32 v180, 16, v58
	v_and_b32_e32 v181, 0xffff0000, v58
	v_pk_add_f32 v[204:205], v[204:205], v[180:181]
	v_lshlrev_b32_e32 v180, 16, v59
	v_and_b32_e32 v181, 0xffff0000, v59
	v_pk_add_f32 v[206:207], v[206:207], v[180:181]
	v_lshlrev_b32_e32 v180, 16, v60
	v_and_b32_e32 v181, 0xffff0000, v60
	v_pk_add_f32 v[208:209], v[208:209], v[180:181]
	v_lshlrev_b32_e32 v180, 16, v61
	v_and_b32_e32 v181, 0xffff0000, v61
	v_pk_add_f32 v[210:211], v[210:211], v[180:181]
	v_lshlrev_b32_e32 v180, 16, v62
	v_and_b32_e32 v181, 0xffff0000, v62
	v_pk_add_f32 v[212:213], v[212:213], v[180:181]
	v_lshlrev_b32_e32 v180, 16, v63
	v_and_b32_e32 v181, 0xffff0000, v63
	v_pk_add_f32 v[214:215], v[214:215], v[180:181]
	v_lshlrev_b32_e32 v180, 16, v64
	v_and_b32_e32 v181, 0xffff0000, v64
	v_pk_add_f32 v[200:201], v[200:201], v[180:181]
	v_lshlrev_b32_e32 v180, 16, v65
	v_and_b32_e32 v181, 0xffff0000, v65
	v_pk_add_f32 v[202:203], v[202:203], v[180:181]
	v_lshlrev_b32_e32 v180, 16, v66
	v_and_b32_e32 v181, 0xffff0000, v66
	v_pk_add_f32 v[204:205], v[204:205], v[180:181]
	v_lshlrev_b32_e32 v180, 16, v67
	v_and_b32_e32 v181, 0xffff0000, v67
	v_pk_add_f32 v[206:207], v[206:207], v[180:181]
	v_lshlrev_b32_e32 v180, 16, v68
	v_and_b32_e32 v181, 0xffff0000, v68
	v_pk_add_f32 v[208:209], v[208:209], v[180:181]
	v_lshlrev_b32_e32 v180, 16, v69
	v_and_b32_e32 v181, 0xffff0000, v69
	v_pk_add_f32 v[210:211], v[210:211], v[180:181]
	v_lshlrev_b32_e32 v180, 16, v70
	v_and_b32_e32 v181, 0xffff0000, v70
	v_pk_add_f32 v[212:213], v[212:213], v[180:181]
	v_lshlrev_b32_e32 v180, 16, v71
	v_and_b32_e32 v181, 0xffff0000, v71
	v_pk_add_f32 v[214:215], v[214:215], v[180:181]
	v_lshlrev_b32_e32 v180, 16, v72
	v_and_b32_e32 v181, 0xffff0000, v72
	v_pk_add_f32 v[200:201], v[200:201], v[180:181]
	v_lshlrev_b32_e32 v180, 16, v73
	v_and_b32_e32 v181, 0xffff0000, v73
	v_pk_add_f32 v[202:203], v[202:203], v[180:181]
	v_lshlrev_b32_e32 v180, 16, v74
	v_and_b32_e32 v181, 0xffff0000, v74
	v_pk_add_f32 v[204:205], v[204:205], v[180:181]
	v_lshlrev_b32_e32 v180, 16, v75
	v_and_b32_e32 v181, 0xffff0000, v75
	v_pk_add_f32 v[206:207], v[206:207], v[180:181]
	v_lshlrev_b32_e32 v180, 16, v76
	v_and_b32_e32 v181, 0xffff0000, v76
	v_pk_add_f32 v[208:209], v[208:209], v[180:181]
	v_lshlrev_b32_e32 v180, 16, v77
	v_and_b32_e32 v181, 0xffff0000, v77
	v_pk_add_f32 v[210:211], v[210:211], v[180:181]
	v_lshlrev_b32_e32 v180, 16, v78
	v_and_b32_e32 v181, 0xffff0000, v78
	v_pk_add_f32 v[212:213], v[212:213], v[180:181]
	v_lshlrev_b32_e32 v180, 16, v79
	v_and_b32_e32 v181, 0xffff0000, v79
	v_pk_add_f32 v[214:215], v[214:215], v[180:181]
	v_lshlrev_b32_e32 v180, 16, v80
	v_and_b32_e32 v181, 0xffff0000, v80
	v_pk_add_f32 v[200:201], v[200:201], v[180:181]
	v_lshlrev_b32_e32 v180, 16, v81
	v_and_b32_e32 v181, 0xffff0000, v81
	v_pk_add_f32 v[202:203], v[202:203], v[180:181]
	v_lshlrev_b32_e32 v180, 16, v82
	v_and_b32_e32 v181, 0xffff0000, v82
	v_pk_add_f32 v[204:205], v[204:205], v[180:181]
	v_lshlrev_b32_e32 v180, 16, v83
	v_and_b32_e32 v181, 0xffff0000, v83
	v_pk_add_f32 v[206:207], v[206:207], v[180:181]
	v_lshlrev_b32_e32 v180, 16, v84
	v_and_b32_e32 v181, 0xffff0000, v84
	v_pk_add_f32 v[208:209], v[208:209], v[180:181]
	v_lshlrev_b32_e32 v180, 16, v85
	v_and_b32_e32 v181, 0xffff0000, v85
	v_pk_add_f32 v[210:211], v[210:211], v[180:181]
	v_lshlrev_b32_e32 v180, 16, v86
	v_and_b32_e32 v181, 0xffff0000, v86
	v_pk_add_f32 v[212:213], v[212:213], v[180:181]
	v_lshlrev_b32_e32 v180, 16, v87
	v_and_b32_e32 v181, 0xffff0000, v87
	v_pk_add_f32 v[214:215], v[214:215], v[180:181]
	v_mov_b32_e32 v182, 0
	v_mul_f32_e32 v180, v200, v200
	v_fmac_f32_e32 v180, v201, v201
	v_mul_f32_e32 v181, v202, v202
	v_fmac_f32_e32 v181, v203, v203
	v_add_f32_e32 v180, v180, v181
	v_add_f32_e32 v182, v182, v180
	v_mul_f32_e32 v180, v204, v204
	v_fmac_f32_e32 v180, v205, v205
	v_mul_f32_e32 v181, v206, v206
	v_fmac_f32_e32 v181, v207, v207
	v_add_f32_e32 v180, v180, v181
	v_add_f32_e32 v182, v182, v180
	v_mul_f32_e32 v180, v208, v208
	v_fmac_f32_e32 v180, v209, v209
	v_mul_f32_e32 v181, v210, v210
	v_fmac_f32_e32 v181, v211, v211
	v_add_f32_e32 v180, v180, v181
	v_add_f32_e32 v182, v182, v180
	v_mul_f32_e32 v180, v212, v212
	v_fmac_f32_e32 v180, v213, v213
	v_mul_f32_e32 v181, v214, v214
	v_fmac_f32_e32 v181, v215, v215
	v_add_f32_e32 v180, v180, v181
	v_add_f32_e32 v182, v182, v180
	v_xor_b32_e32 v183, 4, v3
	ds_bpermute_b32 v184, v183, v182
	s_waitcnt lgkmcnt(0)
; DI void final_norm(const Params& P, int G, int wave, int lane, float* dst) {
;     ...
;         const float rs = rsqrtf(wave_sum(s) * (1.0f / DM) + EPS);
; #pragma unroll
;         for (int j = 0; j < 4; ++j) *(f32x4*)(dst + (size_t)m * DM + 4 * lane + 256 * j) = v[j] * rs * *(const f32x4*)(P.norm_f + 4 * lane + 256 * j);
;     }
	v_add_f32_e32 v182, v182, v184
	v_xor_b32_e32 v183, 8, v3
	ds_bpermute_b32 v184, v183, v182
	s_waitcnt lgkmcnt(0)
	v_add_f32_e32 v182, v182, v184
	v_xor_b32_e32 v183, 16, v3
	ds_bpermute_b32 v184, v183, v182
	s_waitcnt lgkmcnt(0)
	v_add_f32_e32 v182, v182, v184
	v_xor_b32_e32 v183, 32, v3
	ds_bpermute_b32 v184, v183, v182
	s_waitcnt lgkmcnt(0)
	v_add_f32_e32 v182, v182, v184
	v_xor_b32_e32 v183, 64, v3
	ds_bpermute_b32 v184, v183, v182
	s_waitcnt lgkmcnt(0)
	v_add_f32_e32 v182, v182, v184
	v_xor_b32_e32 v183, 128, v3
	ds_bpermute_b32 v184, v183, v182
	s_waitcnt lgkmcnt(0)
	v_add_f32_e32 v182, v182, v184
	v_mov_b32_e32 v185, 0x358637bd
	v_fmamk_f32 v182, v182, 0x3a800000, v185
	s_mov_b32 s0, 0x800000
	v_mul_f32_e32 v184, 0x4b800000, v182
	v_cmp_gt_f32_e32 vcc, s0, v182
	s_nop 1
	v_cndmask_b32_e32 v182, v182, v184, vcc
	v_rsq_f32_e32 v182, v182
	s_nop 0
	v_mul_f32_e32 v184, 0x45800000, v182
	v_cndmask_b32_e32 v186, v182, v184, vcc
	v_pk_mul_f32 v[200:201], v[200:201], v[186:187] op_sel_hi:[1,0]
	v_pk_mul_f32 v[202:203], v[202:203], v[186:187] op_sel_hi:[1,0]
	v_pk_mul_f32 v[200:201], v[160:161], v[200:201]
	v_pk_mul_f32 v[202:203], v[162:163], v[202:203]
	global_store_dwordx4 v1, v[200:203], s[8:9]
	v_pk_mul_f32 v[204:205], v[204:205], v[186:187] op_sel_hi:[1,0]
	v_pk_mul_f32 v[206:207], v[206:207], v[186:187] op_sel_hi:[1,0]
	v_pk_mul_f32 v[204:205], v[164:165], v[204:205]
	v_pk_mul_f32 v[206:207], v[166:167], v[206:207]
	global_store_dwordx4 v1, v[204:207], s[8:9] offset:1024
	v_pk_mul_f32 v[208:209], v[208:209], v[186:187] op_sel_hi:[1,0]
	v_pk_mul_f32 v[210:211], v[210:211], v[186:187] op_sel_hi:[1,0]
	v_pk_mul_f32 v[208:209], v[168:169], v[208:209]
	v_pk_mul_f32 v[210:211], v[170:171], v[210:211]
	global_store_dwordx4 v1, v[208:211], s[8:9] offset:2048
	v_pk_mul_f32 v[212:213], v[212:213], v[186:187] op_sel_hi:[1,0]
	v_pk_mul_f32 v[214:215], v[214:215], v[186:187] op_sel_hi:[1,0]
	v_pk_mul_f32 v[212:213], v[172:173], v[212:213]
	v_pk_mul_f32 v[214:215], v[174:175], v[214:215]
	global_store_dwordx4 v1, v[212:215], s[8:9] offset:3072
	s_add_i32 s64, s64, s66
	s_add_i32 s0, s64, 0x4000
	s_cmpk_lt_i32 s0, 0x4400
	s_cbranch_scc1 .Lp8_row
